# selection candidate stage: initial bracket from the half lists' min/max (lo = max(s0min+s1max, s0max+s1min) relaxed by a quarter of the width, hi = s0max+s1max) instead of a 64-value min3/max3 chain
# speedup vs baseline: 1.2203x; 1.0021x over previous
; __device__ __forceinline__ void peer_phase(const Ctx& C, const bf16* PQ, const bf16* SK  , const unsigned char* ED, const unsigned char* EU, const bf16* HB  , bf16* XBN  , float* RSS, float* xio, const float* gfinal, bool last, float* SELG, int* SELI) {
;     ...
;             float s0[4], s1[16]; int i0[4];
; #pragma unroll
;             for (int a = 0; a < 4; ++a) { s0[a] = ls[(0 * 16 + i) * 16 + 4 * g + a]; i0[a] = li[(0 * 16 + i) * 16 + 4 * g + a]; }
; #pragma unroll
;             for (int bb = 0; bb < 16; ++bb) s1[bb] = ls[(1 * 16 + i) * 16 + bb];
;             float cs[64];
; #pragma unroll
;             for (int a = 0; a < 4; ++a)
; #pragma unroll
;                 for (int bb = 0; bb < 16; ++bb) cs[a * 16 + bb] = s0[a] + s1[bb];
;             float lo, hi;
;             { float mn = cs[0], mx = cs[0];
; #pragma unroll
;               for (int r = 1; r < 64; ++r) { mn = fminf(mn, cs[r]); mx = fmaxf(mx, cs[r]); }
;               mn = fminf(mn, __shfl_xor(mn, 16)); mn = fminf(mn, __shfl_xor(mn, 32)); mx = fmaxf(mx, __shfl_xor(mx, 16)); mx = fmaxf(mx, __shfl_xor(mx, 32));
;               lo = mn; hi = mx; }
.LBB0_178:
	ds_read_b128 v[16:19], v93 offset:1072
	ds_read_b128 v[22:25], v93 offset:1024
	ds_read_b128 v[156:159], v125
	ds_read_b128 v[40:43], v93 offset:1056
	ds_read_b128 v[44:47], v93 offset:1040
	s_waitcnt lgkmcnt(4)
	v_mov_b32_e32 v26, v19
	s_waitcnt lgkmcnt(3)
	v_mov_b32_e32 v27, v22
	s_waitcnt lgkmcnt(2)
	v_add_f32_e32 v154, v156, v23
	v_add_f32_e32 v20, v156, v22
	v_add_f32_e32 v153, v156, v24
	v_add_f32_e32 v152, v156, v25
	s_waitcnt lgkmcnt(0)
	v_max_f32_e32 v200, v22, v23
	v_min_f32_e32 v201, v22, v23
	v_max3_f32 v200, v200, v24, v25
	v_min3_f32 v201, v201, v24, v25
	v_max3_f32 v200, v200, v44, v45
	v_min3_f32 v201, v201, v44, v45
	v_max3_f32 v200, v200, v46, v47
	v_min3_f32 v201, v201, v46, v47
	v_max3_f32 v200, v200, v40, v41
	v_min3_f32 v201, v201, v40, v41
	v_max3_f32 v200, v200, v42, v43
	v_min3_f32 v201, v201, v42, v43
	v_max3_f32 v200, v200, v16, v17
	v_min3_f32 v201, v201, v16, v17
	v_max3_f32 v200, v200, v18, v19
	v_min3_f32 v201, v201, v18, v19
	v_add_f32_e32 v150, v156, v44
	v_add_f32_e32 v33, v156, v43
	v_add_f32_e32 v32, v156, v16
	v_add_f32_e32 v142, v157, v44
	v_add_f32_e32 v132, v157, v43
	v_add_f32_e32 v131, v157, v16
	v_add_f32_e32 v67, v158, v44
	v_add_f32_e32 v60, v158, v43
	v_add_f32_e32 v59, v158, v16
	v_add_f32_e32 v53, v159, v44
	v_add_f32_e32 v44, v159, v43
	v_add_f32_e32 v43, v159, v16
	v_add_f32_e32 v31, v156, v45
	v_add_f32_e32 v34, v156, v42
	v_add_f32_e32 v148, v156, v17
	v_add_f32_e32 v141, v157, v45
	v_add_f32_e32 v133, v157, v42
	v_add_f32_e32 v130, v157, v17
	v_add_f32_e32 v66, v158, v45
	v_add_f32_e32 v61, v158, v42
	v_add_f32_e32 v58, v158, v17
	v_add_f32_e32 v52, v159, v45
	v_add_f32_e32 v45, v159, v42
	v_add_f32_e32 v42, v159, v17
	v_add_f32_e32 v30, v156, v46
	v_add_f32_e32 v29, v156, v47
	v_add_f32_e32 v28, v156, v40
	v_add_f32_e32 v35, v156, v41
	v_add_f32_e32 v147, v156, v18
	v_pk_add_f32 v[38:39], v[156:157], v[26:27]
	v_add_f32_e32 v146, v157, v23
	v_add_f32_e32 v145, v157, v24
	v_add_f32_e32 v143, v157, v25
	v_add_f32_e32 v139, v157, v46
	v_add_f32_e32 v136, v157, v47
	v_add_f32_e32 v135, v157, v40
	v_add_f32_e32 v134, v157, v41
	v_add_f32_e32 v83, v157, v18
	v_add_f32_e32 v82, v157, v19
	v_add_f32_e32 v71, v158, v22
	v_add_f32_e32 v70, v158, v23
	v_add_f32_e32 v69, v158, v24
	v_add_f32_e32 v68, v158, v25
	v_add_f32_e32 v65, v158, v46
	v_add_f32_e32 v64, v158, v47
	v_add_f32_e32 v63, v158, v40
	v_add_f32_e32 v62, v158, v41
	v_add_f32_e32 v57, v158, v18
	v_pk_add_f32 v[36:37], v[158:159], v[26:27]
	v_add_f32_e32 v56, v159, v23
	v_add_f32_e32 v55, v159, v24
	v_add_f32_e32 v54, v159, v25
	v_add_f32_e32 v51, v159, v46
	v_add_f32_e32 v50, v159, v47
	v_add_f32_e32 v47, v159, v40
	v_add_f32_e32 v46, v159, v41
	v_add_f32_e32 v41, v159, v18
	v_add_f32_e32 v40, v159, v19
	v_min3_f32 v16, v156, v157, v158
	v_max3_f32 v17, v156, v157, v158
	v_min_f32_e32 v16, v16, v159
	v_max_f32_e32 v17, v17, v159
	ds_bpermute_b32 v18, v48, v16
	ds_bpermute_b32 v19, v48, v17
	s_mov_b32 s2, 0
	s_waitcnt lgkmcnt(1)
	v_max_f32_e32 v18, v18, v18
	v_min_f32_e32 v21, v16, v18
	s_waitcnt lgkmcnt(0)
	v_max_f32_e32 v16, v19, v19
	ds_bpermute_b32 v23, v49, v21
	v_max_f32_e32 v22, v17, v16
	ds_bpermute_b32 v24, v49, v22
	ds_read_b128 v[16:19], v125 offset:2304
	s_waitcnt lgkmcnt(2)
	v_max_f32_e32 v23, v23, v23
	v_min_f32_e32 v21, v21, v23
	s_waitcnt lgkmcnt(1)
	v_max_f32_e32 v23, v24, v24
	v_max_f32_e32 v22, v22, v23
	v_add_f32_e32 v23, v21, v200
	v_add_f32_e32 v24, v22, v201
	v_add_f32_e32 v22, v22, v200
	v_max_f32_e32 v21, v23, v24
	v_sub_f32_e32 v23, v22, v21
	v_fmac_f32_e32 v21, 0xbe800000, v23
	s_mov_b64 s[4:5], 0
	s_mov_b32 s2, 0
	s_waitcnt lgkmcnt(0)
